# mixer phase: every workgroup runs its gMLP wave-units after its FIRST attention unit instead of before it (phase body re-entered: attention unit 1, gMLP, rest of the attention queue), so the HBM-bound
# speedup vs baseline: 1.0070x; 1.0052x over previous
.LBB0_20:
	s_add_u32 s4, s96, 0x1b600000
	v_writelane_b32 v251, s4, 16
	s_addc_u32 s4, s97, 0
	s_add_u32 s14, s96, 0x5200000
	v_writelane_b32 v251, s4, 17
	s_addc_u32 s15, s97, 0
	s_lshl_b32 s4, s33, 3
	s_lshl_b32 s18, s65, 3
	v_writelane_b32 v251, s4, 18
	s_add_u32 s4, s96, 0x1f800000
	s_addc_u32 s5, s97, 0
	v_writelane_b32 v251, s4, 19
	s_load_dwordx16 s[68:83], s[0:1], 0x0
	v_and_b32_e32 v0, 63, v224
	v_writelane_b32 v251, s5, 20
	s_add_u32 s4, s96, 0x600000
	s_addc_u32 s5, s97, 0
	v_writelane_b32 v251, s4, 21
	s_add_u32 s98, s96, 0x4200000
	s_waitcnt lgkmcnt(0)
	s_mov_b64 s[86:87], s[82:83]
	v_writelane_b32 v251, s5, 22
	s_addc_u32 s4, s97, 0
	s_add_u32 s50, s96, 0x800000
	s_addc_u32 s56, s97, 0
	v_writelane_b32 v251, s4, 23
	s_add_u32 s4, s96, 0x500000
	s_addc_u32 s5, s97, 0
	v_writelane_b32 v251, s4, 24
	s_lshl_b32 s55, s65, 9
	s_mov_b64 s[84:85], s[80:81]
	v_writelane_b32 v251, s5, 25
	s_lshl_b32 s4, s37, 9
	v_writelane_b32 v251, s4, 26
	s_add_u32 s4, s96, 0x200
	s_addc_u32 s5, s97, 0
	v_writelane_b32 v251, s4, 27
	s_mov_b64 s[82:83], s[78:79]
	s_mov_b64 s[80:81], s[76:77]
	v_writelane_b32 v251, s5, 28
	s_add_u32 s4, s96, 0x1000
	s_addc_u32 s5, s97, 0
	v_writelane_b32 v251, s4, 29
	v_mbcnt_lo_u32_b32 v1, -1, 0
	v_mbcnt_hi_u32_b32 v228, -1, v1
	v_writelane_b32 v251, s5, 30
	s_add_u32 s4, s96, 0x1100
	s_addc_u32 s5, s97, 0
	v_writelane_b32 v251, s4, 31
	s_mov_b32 s90, 0xfffe0000
	v_and_b32_e32 v1, 64, v228
	v_writelane_b32 v251, s5, 32
	s_add_u32 s4, s96, 0x1200
	s_addc_u32 s5, s97, 0
	v_writelane_b32 v251, s4, 33
	v_mov_b32_e32 v193, 0
	v_mov_b32_e32 v225, 0x358637bd
	v_writelane_b32 v251, s5, 34
	s_add_u32 s4, s96, 0x1300
	s_addc_u32 s5, s97, 0
	v_writelane_b32 v251, s4, 35
	s_cmp_eq_u32 s12, 15
	v_mov_b32_e32 v226, 0x260
	v_writelane_b32 v251, s5, 36
	s_cselect_b64 s[4:5], -1, 0
	v_writelane_b32 v251, s4, 37
	s_cmp_eq_u32 s12, 14
	v_mov_b32_e32 v229, 0x3ecc95a3
	v_writelane_b32 v251, s5, 38
	s_cselect_b64 s[4:5], -1, 0
	v_writelane_b32 v251, s4, 39
	s_cmp_eq_u32 s12, 13
	v_add_u32_e32 v231, 64, v1
	v_writelane_b32 v251, s5, 40
	s_cselect_b64 s[4:5], -1, 0
	v_writelane_b32 v251, s4, 41
	s_cmp_eq_u32 s12, 12
	v_xor_b32_e32 v232, 1, v228
	v_writelane_b32 v251, s5, 42
	s_cselect_b64 s[4:5], -1, 0
	v_writelane_b32 v251, s4, 43
	s_cmp_eq_u32 s12, 11
	v_xor_b32_e32 v233, 2, v228
	v_writelane_b32 v251, s5, 44
	s_cselect_b64 s[4:5], -1, 0
	v_writelane_b32 v251, s4, 45
	s_cmp_eq_u32 s12, 10
	v_xor_b32_e32 v234, 4, v228
	v_writelane_b32 v251, s5, 46
	s_cselect_b64 s[4:5], -1, 0
	v_writelane_b32 v251, s4, 47
	s_cmp_eq_u32 s12, 9
	v_xor_b32_e32 v235, 8, v228
	v_writelane_b32 v251, s5, 48
	s_cselect_b64 s[4:5], -1, 0
	v_writelane_b32 v251, s4, 49
	s_cmp_eq_u32 s12, 8
	v_xor_b32_e32 v236, 16, v228
	v_writelane_b32 v251, s5, 50
	s_cselect_b64 s[4:5], -1, 0
	v_writelane_b32 v251, s4, 51
	s_cmp_eq_u32 s12, 7
	v_xor_b32_e32 v237, 32, v228
	v_writelane_b32 v251, s5, 52
	s_cselect_b64 s[4:5], -1, 0
	v_writelane_b32 v251, s4, 53
	s_cmp_eq_u32 s12, 6
	v_mov_b32_e32 v194, 0x3a800000
	v_writelane_b32 v251, s5, 54
	s_cselect_b64 s[4:5], -1, 0
	v_writelane_b32 v251, s4, 55
	s_cmp_eq_u32 s12, 5
	v_mov_b32_e32 v238, 0xff800000
	v_writelane_b32 v251, s5, 56
	s_cselect_b64 s[4:5], -1, 0
	v_writelane_b32 v251, s4, 57
	s_cmp_eq_u32 s12, 4
	v_mov_b64_e32 v[248:249], 0x700
	v_writelane_b32 v251, s5, 58
	s_cselect_b64 s[4:5], -1, 0
	v_writelane_b32 v251, s4, 59
	s_cmp_eq_u32 s12, 3
	v_mov_b64_e32 v[198:199], 0x6ff
	v_writelane_b32 v251, s5, 60
	s_cselect_b64 s[4:5], -1, 0
	v_writelane_b32 v251, s4, 61
	s_cmp_eq_u32 s12, 2
	v_mov_b32_e32 v239, 0xff0
	v_writelane_b32 v251, s5, 62
	s_cselect_b64 s[4:5], -1, 0
	v_writelane_b32 v251, s4, 63
	s_cmp_eq_u32 s12, 1
	v_mov_b32_e32 v240, 0x6000
	v_writelane_b32 v252, s5, 0
	s_cselect_b64 s[4:5], -1, 0
	v_writelane_b32 v252, s4, 1
	s_cmp_eq_u32 s12, 0
	v_mov_b32_e32 v241, 0x7f800000
	v_writelane_b32 v252, s5, 2
	s_cselect_b64 s[4:5], -1, 0
	v_writelane_b32 v252, s4, 3
	v_mov_b32_e32 v242, 0x30000
	v_mov_b32_e32 v243, 0x18000
	v_writelane_b32 v252, s5, 4
	s_lshl_b32 s4, s12, 8
	s_add_u32 s4, s96, s4
	s_addc_u32 s5, s97, 0
	s_add_u32 s6, s4, 0x1400
	s_addc_u32 s7, s5, 0
	v_writelane_b32 v252, s6, 5
	s_add_u32 s4, s4, 0x2400
	s_addc_u32 s5, s5, 0
	v_writelane_b32 v252, s7, 6
	v_writelane_b32 v252, s4, 7
	s_movk_i32 s59, 0x1000
	s_mov_b32 s61, 0xf800000
	v_writelane_b32 v252, s5, 8
	s_add_u32 s4, s96, 0x3400
	s_addc_u32 s5, s97, 0
	v_writelane_b32 v252, s4, 9
	s_mov_b32 s63, 0xc000
	s_movk_i32 s99, 0x6000
	v_writelane_b32 v252, s5, 10
	s_add_u32 s4, s96, 0x3500
	s_addc_u32 s5, s97, 0
	v_writelane_b32 v252, s4, 11
	s_movk_i32 s57, 0x2000
	s_mov_b32 s47, 0x41a00000
	v_writelane_b32 v252, s5, 12
	s_add_u32 s4, s96, 0x9200000
	s_addc_u32 s5, s97, 0
	v_writelane_b32 v252, s4, 13
	s_mov_b32 s67, 0xb2a5705f
	s_mov_b32 s35, 0x3f317218
	v_writelane_b32 v252, s5, 14
	s_add_u32 s4, s96, 0xb200000
	s_addc_u32 s5, s97, 0
	v_writelane_b32 v252, s4, 15
	s_mov_b32 s51, 0x33800000
	s_mov_b64 s[42:43], 0x80
	v_writelane_b32 v252, s5, 16
	s_add_u32 s4, s96, 0xd200000
	s_addc_u32 s5, s97, 0
	v_writelane_b32 v252, s4, 17
	s_add_u32 s10, s96, 0x17200000
	s_addc_u32 s11, s97, 0
	v_writelane_b32 v252, s5, 18
	v_writelane_b32 v252, s10, 19
	s_add_u32 s4, s96, 0x1b200000
	s_addc_u32 s5, s97, 0
	v_writelane_b32 v252, s11, 20
	v_writelane_b32 v252, s4, 21
	s_mov_b64 s[88:89], 0x40000
	s_mov_b64 s[48:49], 0x60000
	v_writelane_b32 v252, s5, 22
	s_add_u32 s4, s96, 0xf200000
	s_addc_u32 s5, s97, 0
	v_writelane_b32 v252, s4, 23
	s_mov_b32 s91, -1
	s_mov_b32 s54, 0xbfb8aa3b
	v_writelane_b32 v252, s5, 24
	s_add_u32 s4, s96, 0x3c00
	v_writelane_b32 v252, s4, 25
	s_addc_u32 s4, s97, 0
	v_writelane_b32 v252, s4, 26
	s_add_u32 s4, s96, 0x3800
	v_writelane_b32 v252, s4, 27
	s_addc_u32 s4, s97, 0
	v_writelane_b32 v252, s4, 28
	s_ashr_i32 s4, s37, 31
	v_writelane_b32 v252, s4, 29
	s_lshr_b32 s4, s4, 29
	s_add_i32 s4, s37, s4
	s_ashr_i32 s5, s4, 3
	s_and_b32 s4, s4, -8
	s_sub_i32 s4, s37, s4
	s_ashr_i32 s6, s65, 3
	s_mul_i32 s6, s6, s4
	s_add_i32 s6, s6, s5
	s_add_u32 s8, s96, 0x1b400000
	s_addc_u32 s9, s97, 0
	v_writelane_b32 v252, s8, 30
	s_add_u32 s46, s96, 0x11200000
	s_addc_u32 s7, s97, 0
	v_writelane_b32 v252, s9, 31
	v_writelane_b32 v252, s7, 32
	s_add_u32 s7, s96, 0x13200000
	v_writelane_b32 v252, s7, 33
	s_addc_u32 s7, s97, 0
	v_writelane_b32 v252, s7, 34
	s_add_u32 s7, s96, 0x15200000
	v_writelane_b32 v252, s7, 35
	s_addc_u32 s7, s97, 0
	v_writelane_b32 v252, s7, 36
	s_add_u32 s7, s96, 0x17200800
	v_writelane_b32 v252, s7, 37
	s_addc_u32 s7, s97, 0
	s_cmp_lt_i32 s37, 64
	s_cselect_b64 s[8:9], -1, 0
	s_add_u32 s30, s96, 0x700000
	v_writelane_b32 v252, s7, 38
	s_addc_u32 s31, s97, 0
	v_writelane_b32 v252, s8, 39
	s_cmpk_lt_i32 s37, 0x700
	s_mov_b32 s58, 0x3e6d3388
	v_writelane_b32 v252, s9, 40
	s_cselect_b64 s[8:9], -1, 0
	s_ashr_i32 s29, s65, 31
	v_writelane_b32 v252, s8, 41
	s_cmpk_lt_i32 s37, 0x200
	s_mov_b32 s60, 0x3f07dc22
	v_writelane_b32 v252, s9, 42
	s_cselect_b64 s[8:9], -1, 0
	s_lshl_b32 s7, s4, 6
	v_writelane_b32 v252, s8, 43
	s_cmpk_lt_i32 s33, 0x100
	s_mov_b32 s62, 0x3f35f0e3
	v_writelane_b32 v252, s9, 44
	s_cselect_b64 s[8:9], -1, 0
	s_and_b64 s[2:3], s[2:3], exec
	v_writelane_b32 v252, s8, 45
	s_cselect_b32 s2, s6, s37
	s_cmpk_lt_i32 s2, 0x400
	v_writelane_b32 v252, s9, 46
	v_writelane_b32 v252, s2, 47
	s_cselect_b64 s[2:3], -1, 0
	v_writelane_b32 v252, s2, 48
	s_cmp_lt_i32 s4, 0
	s_mov_b32 s64, 0xbe11a98e
	v_writelane_b32 v252, s3, 49
	s_movk_i32 s2, 0xe1
	s_cselect_b32 s2, s2, 0xe0
	s_mul_i32 s2, s4, s2
	s_mulk_i32 s4, 0x41
	s_cselect_b32 s3, s4, s7
	s_add_i32 s2, s2, s5
	s_mul_hi_i32 s4, s2, 0x92492493
	s_add_i32 s4, s4, s2
	s_lshr_b32 s6, s4, 31
	s_ashr_i32 s4, s4, 7
	s_add_i32 s4, s4, s6
	s_mul_i32 s6, s4, 0xe0
	s_sub_i32 s2, s2, s6
	s_add_i32 s3, s3, s5
	s_bfe_u32 s6, s2, 0x3001c
	s_ashr_i32 s5, s3, 31
	s_add_i32 s6, s2, s6
	s_lshr_b32 s5, s5, 26
	s_and_b32 s7, s6, 0xfff8
	s_add_i32 s5, s3, s5
	s_sub_i32 s2, s2, s7
	s_and_b32 s7, s5, 0xffc0
	s_sub_i32 s3, s3, s7
	s_bfe_i32 s7, s3, 0x80000
	s_bfe_u32 s7, s7, 0x3000c
	s_add_i32 s7, s3, s7
	s_and_b32 s8, s7, 0xf8
	s_lshl_b32 s4, s4, 3
	s_sext_i32_i16 s2, s2
	s_sub_i32 s3, s3, s8
	s_add_i32 s8, s4, s2
	s_ashr_i32 s2, s5, 6
	s_bfe_i32 s4, s7, 0x80000
	s_lshl_b32 s2, s2, 3
	s_sext_i32_i16 s4, s4
	s_sext_i32_i8 s3, s3
	s_add_i32 s12, s2, s3
	s_ashr_i32 s2, s4, 3
	v_writelane_b32 v252, s2, 50
	s_lshr_b32 s2, s4, 3
	s_bfe_i64 s[2:3], s[2:3], 0x100000
	s_lshl_b64 s[2:3], s[2:3], 20
	s_sext_i32_i16 s6, s6
	v_writelane_b32 v252, s2, 51
	s_mov_b32 s4, s12
	s_ashr_i32 s13, s12, 31
	v_writelane_b32 v252, s3, 52
	s_ashr_i32 s2, s6, 3
	v_writelane_b32 v252, s2, 53
	v_writelane_b32 v252, s4, 54
	s_lshr_b32 s2, s6, 3
	s_mov_b32 s66, 0x3e027906
	v_writelane_b32 v252, s5, 55
	s_lshl_b64 s[4:5], s[12:13], 20
	s_add_u32 s4, s10, s4
	s_addc_u32 s5, s11, s5
	s_add_u32 s6, s4, 0x80000
	v_writelane_b32 v252, s4, 56
	s_addc_u32 s7, s5, 0
	s_bfe_i64 s[2:3], s[2:3], 0x100000
	v_writelane_b32 v252, s5, 57
	v_writelane_b32 v252, s6, 58
	s_lshl_b64 s[2:3], s[2:3], 20
	s_ashr_i32 s9, s8, 31
	v_writelane_b32 v252, s7, 59
	v_writelane_b32 v252, s2, 60
	s_mov_b32 s34, 0xbf38aa3b
	s_nop 0
	v_writelane_b32 v252, s3, 61
	s_mov_b32 s2, s8
	v_writelane_b32 v252, s2, 62
	s_nop 1
	v_writelane_b32 v252, s3, 63
	s_lshl_b64 s[2:3], s[8:9], 20
	s_add_u32 s2, s14, s2
	v_writelane_b32 v253, s14, 0
	s_addc_u32 s3, s15, s3
	s_add_u32 s4, s2, 0x80000
	v_writelane_b32 v253, s15, 1
	v_writelane_b32 v253, s2, 2
	s_addc_u32 s5, s3, 0
	s_ashr_i32 s19, s18, 31
	v_writelane_b32 v253, s3, 3
	v_writelane_b32 v253, s4, 4
	s_lshl_b64 s[44:45], s[18:19], 12
	s_nop 0
	v_writelane_b32 v253, s5, 5
	s_load_dwordx4 s[4:7], s[0:1], 0x60
	s_waitcnt lgkmcnt(0)
	s_add_u32 s2, s6, 0x1000
	v_writelane_b32 v253, s2, 6
	s_addc_u32 s2, s7, 0
	s_lshl_b64 s[12:13], s[18:19], 13
	s_add_u32 s0, s74, 0x30000
	v_writelane_b32 v253, s2, 7
	s_addc_u32 s1, s75, 0
	v_writelane_b32 v253, s0, 8
	s_mov_b64 s[76:77], s[72:73]
	s_mov_b64 s[74:75], s[70:71]
	v_writelane_b32 v253, s1, 9
	s_lshl_b32 s0, s33, 9
	v_writelane_b32 v253, s0, 10
	s_lshl_b32 s0, s33, 6
	v_writelane_b32 v253, s0, 11
	s_lshl_b32 s0, s65, 6
	v_writelane_b32 v253, s0, 12
	s_add_u32 s0, s78, 0x7000
	v_writelane_b32 v253, s0, 13
	s_mov_b64 s[72:73], s[68:69]
	v_writelane_b32 v253, s72, 14
	s_addc_u32 s0, s79, 0
	s_add_i32 s68, 0, 0x18820
	v_writelane_b32 v253, s73, 15
	v_writelane_b32 v253, s74, 16
	v_writelane_b32 v253, s75, 17
	v_writelane_b32 v253, s76, 18
	v_writelane_b32 v253, s77, 19
	v_writelane_b32 v253, s78, 20
	v_writelane_b32 v253, s79, 21
	v_writelane_b32 v253, s80, 22
	v_writelane_b32 v253, s81, 23
	v_writelane_b32 v253, s82, 24
	v_writelane_b32 v253, s83, 25
	v_writelane_b32 v253, s84, 26
	v_writelane_b32 v253, s85, 27
	v_writelane_b32 v253, s86, 28
	v_writelane_b32 v253, s87, 29
	v_writelane_b32 v253, s0, 30
	s_add_i32 s0, 0, 0x24000
	v_writelane_b32 v253, s0, 31
	s_add_i32 s0, 0, 0x24004
	v_writelane_b32 v253, s0, 32
	s_add_i32 s0, 0, 0x18800
	v_writelane_b32 v253, s0, 33
	s_add_i32 s0, 0, 0x18810
	v_writelane_b32 v253, s0, 34
	s_add_i32 s0, 0, 0x11000
	v_writelane_b32 v253, s0, 35
	s_add_i32 s0, 0, 0x13000
	v_writelane_b32 v253, s0, 36
	v_cmp_eq_u32_e64 s[0:1], 0, v0
	s_add_i32 s72, 0, 0x20000
	s_mov_b32 s69, 0x42ce8ed0
	v_writelane_b32 v253, s0, 37
	s_mov_b32 s73, 0xc2b17218
	s_mov_b32 s75, 0x7f800000
	v_writelane_b32 v253, s1, 38
	s_mov_b32 s0, s18
	v_writelane_b32 v253, s0, 39
	s_mov_b32 s77, 0x3f2aaaab
	s_mov_b32 s79, 0
	v_writelane_b32 v253, s1, 40
	v_writelane_b32 v253, s29, 41
	v_writelane_b32 v253, s44, 42
	s_nop 1
	v_writelane_b32 v253, s45, 43
	v_writelane_b32 v253, s12, 44
	s_nop 1
	v_writelane_b32 v253, s13, 45
	v_writelane_b32 v253, s37, 46
	v_writelane_b32 v253, s50, 47
	v_writelane_b32 v253, s56, 48
	v_writelane_b32 v253, s68, 49
	v_writelane_b32 v253, s72, 50
	s_mov_b32 s0, 0
	s_nop 0
	v_writelane_b32 v255, s0, 61
	s_branch .LBB0_24

.LBB0_122:
	s_or_b64 exec, exec, s[2:3]
	global_load_dwordx4 v[6:9], v[2:3], off
	v_readlane_b32 s0, v251, 18
	v_lshl_add_u32 v0, v0, 2, 0
	s_add_i32 s16, s83, s0
	v_and_b32_e32 v157, 31, v200
	v_add_u32_e32 v0, 0x22000, v0
	s_cmpk_gt_i32 s16, 0x7ff
	s_waitcnt vmcnt(0)
	ds_write_b128 v0, v[6:9]
	s_waitcnt lgkmcnt(0)
	s_barrier
	s_cbranch_scc1 .LBB0_126
	v_readlane_b32 s0, v255, 61
	s_nop 3
	s_bitcmp1_b32 s0, 0
	s_cbranch_scc1 .LBB0_126
	v_readlane_b32 s0, v252, 27
	v_lshrrev_b32_e32 v0, 5, v244
	v_readlane_b32 s0, v251, 23
	v_lshlrev_b32_e32 v1, 3, v0
	s_lshl_b64 s[0:1], s[94:95], 18
	v_readlane_b32 s2, v251, 21
	v_or_b32_e32 v3, 7, v1
	v_readlane_b32 s3, v251, 22
	s_add_u32 s0, s2, s0
	v_cmp_gt_u32_e64 s[84:85], v3, v157
	v_or_b32_e32 v3, 6, v1
	s_addc_u32 s1, s3, s1
	v_lshlrev_b32_e32 v192, 4, v0
	v_cmp_gt_u32_e64 s[86:87], v3, v157
	v_or_b32_e32 v3, 5, v1
	v_lshl_add_u64 v[158:159], s[0:1], 0, v[192:193]
	v_cmp_gt_u32_e64 s[0:1], v3, v157
	v_or_b32_e32 v3, 4, v1
	v_or_b32_e32 v2, 32, v244
	v_writelane_b32 v253, s0, 53
	v_readlane_b32 s4, v251, 4
	s_lshl_b64 s[2:3], s[94:95], 12
	v_writelane_b32 v253, s1, 54
	v_cmp_gt_u32_e64 s[0:1], v3, v157
	v_or_b32_e32 v3, 3, v1
	v_readlane_b32 s6, v251, 6
	v_writelane_b32 v253, s0, 55
	v_readlane_b32 s7, v251, 7
	s_add_u32 s12, s6, s2
	v_writelane_b32 v253, s1, 56
	v_cmp_gt_u32_e64 s[0:1], v3, v157
	v_or_b32_e32 v3, 2, v1
	s_mul_i32 s2, s83, 0x4400
	v_writelane_b32 v253, s0, 57
	s_addc_u32 s13, s7, s3
	s_add_i32 s2, s2, 0
	v_writelane_b32 v253, s1, 58
	v_cmp_gt_u32_e64 s[0:1], v3, v157
	v_or_b32_e32 v3, 23, v1
	v_add_u32_e32 v161, s2, v4
	v_writelane_b32 v253, s0, 59
	v_or_b32_e32 v4, 0x47, v1
	v_lshl_add_u32 v165, v0, 6, s2
	v_writelane_b32 v253, s1, 60
	v_cmp_lt_u32_e64 s[0:1], v1, v157
	v_and_b32_e32 v0, 7, v200
	v_add_u32_e32 v163, s2, v192
	v_writelane_b32 v253, s0, 61
	v_lshlrev_b32_e32 v167, 3, v0
	v_lshl_add_u32 v0, v0, 5, s2
	v_writelane_b32 v253, s1, 62
	v_cmp_gt_u32_e64 s[0:1], v3, v157
	v_or_b32_e32 v3, 22, v1
	s_lshl_b32 s14, s83, 6
	v_writelane_b32 v253, s0, 63
	v_readlane_b32 s5, v251, 5
	v_lshrrev_b32_e32 v160, 3, v244
	v_writelane_b32 v254, s1, 0
	v_cmp_gt_u32_e64 s[0:1], v3, v157
	v_or_b32_e32 v3, 21, v1
	v_readlane_b32 s8, v251, 8
	v_writelane_b32 v254, s0, 1
	v_readlane_b32 s9, v251, 9
	v_readlane_b32 s10, v251, 10
	v_writelane_b32 v254, s1, 2
	v_cmp_gt_u32_e64 s[0:1], v3, v157
	v_or_b32_e32 v3, 20, v1
	v_readlane_b32 s11, v251, 11
	v_writelane_b32 v254, s0, 3
	v_mul_u32_u24_e32 v171, 0x110, v2
	v_cmp_gt_u32_e64 s[52:53], v1, v157
	v_writelane_b32 v254, s1, 4
	v_cmp_gt_u32_e64 s[0:1], v3, v157
	v_or_b32_e32 v3, 19, v1
	v_readlane_b32 s36, v252, 13
	v_writelane_b32 v254, s0, 5
	v_readlane_b32 s80, v252, 17
	v_readlane_b32 s28, v252, 15
	v_writelane_b32 v254, s1, 6
	v_cmp_gt_u32_e64 s[0:1], v3, v157
	v_or_b32_e32 v3, 18, v1
	v_readlane_b32 s4, v252, 19
	v_writelane_b32 v254, s0, 7
	s_mov_b32 s27, s46
	v_lshlrev_b32_e32 v156, 1, v244
	v_writelane_b32 v254, s1, 8
	v_cmp_gt_u32_e64 s[0:1], v3, v157
	v_or_b32_e32 v3, 17, v1
	v_or_b32_e32 v162, 64, v160
	v_writelane_b32 v254, s0, 9
	v_mul_u32_u24_e32 v169, 0x110, v157
	v_or_b32_e32 v164, 8, v160
	v_writelane_b32 v254, s1, 10
	v_cmp_gt_u32_e64 s[0:1], v3, v157
	v_or_b32_e32 v3, 16, v1
	v_or_b32_e32 v166, 16, v160
	v_writelane_b32 v254, s0, 11
	v_or_b32_e32 v168, 24, v160
	v_or_b32_e32 v170, 32, v160
	v_writelane_b32 v254, s1, 12
	v_cmp_gt_u32_e64 s[0:1], v3, v157
	v_or_b32_e32 v3, 39, v1
	v_or_b32_e32 v172, 40, v160
	v_writelane_b32 v254, s0, 13
	v_or_b32_e32 v174, 48, v160
	v_or_b32_e32 v176, 56, v160
	v_writelane_b32 v254, s1, 14
	v_cmp_gt_u32_e64 s[0:1], v3, v2
	v_or_b32_e32 v3, 38, v1
	v_or_b32_e32 v178, 0x48, v160
	v_writelane_b32 v254, s0, 15
	v_or_b32_e32 v180, 0x50, v160
	v_or_b32_e32 v182, 0x58, v160
	v_writelane_b32 v254, s1, 16
	v_cmp_gt_u32_e64 s[0:1], v3, v2
	v_or_b32_e32 v3, 37, v1
	v_or_b32_e32 v184, 0x60, v160
	v_writelane_b32 v254, s0, 17
	v_or_b32_e32 v186, 0x68, v160
	v_or_b32_e32 v188, 0x70, v160
	v_writelane_b32 v254, s1, 18
	v_cmp_gt_u32_e64 s[0:1], v3, v2
	v_or_b32_e32 v3, 36, v1
	v_or_b32_e32 v190, 0x78, v160
	v_writelane_b32 v254, s0, 19
	v_readlane_b32 s37, v252, 14
	v_readlane_b32 s81, v252, 18
	v_writelane_b32 v254, s1, 20
	v_cmp_gt_u32_e64 s[0:1], v3, v2
	v_or_b32_e32 v3, 35, v1
	v_readlane_b32 s29, v252, 16
	v_writelane_b32 v254, s0, 21
	v_readlane_b32 s5, v252, 20
	v_readlane_b32 s23, v253, 12
	v_writelane_b32 v254, s1, 22
	v_cmp_gt_u32_e64 s[0:1], v3, v2
	v_or_b32_e32 v3, 34, v1
	s_movk_i32 s25, 0x4000
	v_writelane_b32 v254, s0, 23
	s_mov_b32 s44, 0x3a800000
	s_nop 0
	v_writelane_b32 v254, s1, 24
	v_cmp_gt_u32_e64 s[0:1], v3, v2
	v_or_b32_e32 v3, 33, v1
	s_nop 0
	v_writelane_b32 v254, s0, 25
	s_nop 1
	v_writelane_b32 v254, s1, 26
	v_cmp_gt_u32_e64 s[0:1], v3, v2
	v_or_b32_e32 v3, 32, v1
	s_nop 0
	v_writelane_b32 v254, s0, 27
	s_nop 1
	v_writelane_b32 v254, s1, 28
	v_cmp_gt_u32_e64 s[0:1], v3, v2
	v_or_b32_e32 v3, 55, v1
	s_nop 0
	v_writelane_b32 v254, s0, 29
	s_nop 1
	v_writelane_b32 v254, s1, 30
	v_cmp_gt_u32_e64 s[0:1], v3, v2
	v_or_b32_e32 v3, 54, v1
	s_nop 0
	v_writelane_b32 v254, s0, 31
	s_nop 1
	v_writelane_b32 v254, s1, 32
	v_cmp_gt_u32_e64 s[0:1], v3, v2
	v_or_b32_e32 v3, 53, v1
	s_nop 0
	v_writelane_b32 v254, s0, 33
	s_nop 1
	v_writelane_b32 v254, s1, 34
	v_cmp_gt_u32_e64 s[0:1], v3, v2
	v_or_b32_e32 v3, 52, v1
	s_nop 0
	v_writelane_b32 v254, s0, 35
	s_nop 1
	v_writelane_b32 v254, s1, 36
	v_cmp_gt_u32_e64 s[0:1], v3, v2
	v_or_b32_e32 v3, 51, v1
	s_nop 0
	v_writelane_b32 v254, s0, 37
	s_nop 1
	v_writelane_b32 v254, s1, 38
	v_cmp_gt_u32_e64 s[0:1], v3, v2
	v_or_b32_e32 v3, 50, v1
	s_nop 0
	v_writelane_b32 v254, s0, 39
	s_nop 1
	v_writelane_b32 v254, s1, 40
	v_cmp_gt_u32_e64 s[0:1], v3, v2
	v_or_b32_e32 v3, 49, v1
	s_nop 0
	v_writelane_b32 v254, s0, 41
	s_nop 1
	v_writelane_b32 v254, s1, 42
	v_cmp_gt_u32_e64 s[0:1], v3, v2
	v_or_b32_e32 v3, 48, v1
	s_nop 0
	v_writelane_b32 v254, s0, 43
	s_nop 1
	v_writelane_b32 v254, s1, 44
	v_cmp_gt_u32_e64 s[0:1], v3, v2
	v_or_b32_e32 v3, 64, v157
	v_mul_u32_u24_e32 v2, 0x110, v160
	v_writelane_b32 v254, s0, 45
	v_add_u32_e32 v173, v0, v2
	s_nop 0
	v_writelane_b32 v254, s1, 46
	v_cmp_gt_u32_e64 s[0:1], v4, v3
	v_or_b32_e32 v4, 0x46, v1
	s_nop 0
	v_writelane_b32 v254, s0, 47
	s_nop 1
	v_writelane_b32 v254, s1, 48
	v_cmp_gt_u32_e64 s[0:1], v4, v3
	v_or_b32_e32 v4, 0x45, v1
	s_nop 0
	v_writelane_b32 v254, s0, 49
	s_nop 1
	v_writelane_b32 v254, s1, 50
	v_cmp_gt_u32_e64 s[0:1], v4, v3
	v_or_b32_e32 v4, 0x44, v1
	s_nop 0
	v_writelane_b32 v254, s0, 51
	s_nop 1
	v_writelane_b32 v254, s1, 52
	v_cmp_gt_u32_e64 s[0:1], v4, v3
	v_or_b32_e32 v4, 0x43, v1
	s_nop 0
	v_writelane_b32 v254, s0, 53
	s_nop 1
	v_writelane_b32 v254, s1, 54
	v_cmp_gt_u32_e64 s[0:1], v4, v3
	v_or_b32_e32 v4, 0x42, v1
	s_nop 0
	v_writelane_b32 v254, s0, 55
	s_nop 1
	v_writelane_b32 v254, s1, 56
	v_cmp_gt_u32_e64 s[0:1], v4, v3
	v_or_b32_e32 v4, 0x41, v1
	s_nop 0
	v_writelane_b32 v254, s0, 57
	s_nop 1
	v_writelane_b32 v254, s1, 58
	v_cmp_gt_u32_e64 s[0:1], v4, v3
	v_or_b32_e32 v4, 0x57, v1
	s_nop 0
	v_writelane_b32 v254, s0, 59
	s_nop 1
	v_writelane_b32 v254, s1, 60
	v_cmp_gt_u32_e64 s[0:1], v4, v3
	v_or_b32_e32 v4, 0x56, v1
	s_nop 0
	v_writelane_b32 v254, s0, 61
	s_nop 1
	v_writelane_b32 v254, s1, 62
	v_cmp_gt_u32_e64 s[0:1], v4, v3
	v_or_b32_e32 v4, 0x55, v1
	s_nop 0
	v_writelane_b32 v254, s0, 63
	s_nop 1
	v_writelane_b32 v255, s1, 0
	v_cmp_gt_u32_e64 s[0:1], v4, v3
	v_or_b32_e32 v4, 0x54, v1
	s_nop 0
	v_writelane_b32 v255, s0, 1
	s_nop 1
	v_writelane_b32 v255, s1, 2
	v_cmp_gt_u32_e64 s[0:1], v4, v3
	v_or_b32_e32 v4, 0x53, v1
	s_nop 0
	v_writelane_b32 v255, s0, 3
	s_nop 1
	v_writelane_b32 v255, s1, 4
	v_cmp_gt_u32_e64 s[0:1], v4, v3
	v_or_b32_e32 v4, 0x52, v1
	s_nop 0
	v_writelane_b32 v255, s0, 5
	s_nop 1
	v_writelane_b32 v255, s1, 6
	v_cmp_gt_u32_e64 s[0:1], v4, v3
	v_or_b32_e32 v4, 0x51, v1
	s_nop 0
	v_writelane_b32 v255, s0, 7
	s_nop 1
	v_writelane_b32 v255, s1, 8
	v_cmp_gt_u32_e64 s[0:1], v4, v3
	v_or_b32_e32 v4, 0x50, v1
	s_nop 0
	v_writelane_b32 v255, s0, 9
	s_nop 1
	v_writelane_b32 v255, s1, 10
	v_cmp_gt_u32_e64 s[0:1], v4, v3
	v_or_b32_e32 v3, 0x60, v244
	v_or_b32_e32 v4, 0x67, v1
	v_writelane_b32 v255, s0, 11
	s_nop 1
	v_writelane_b32 v255, s1, 12
	v_cmp_gt_u32_e64 s[0:1], v4, v3
	v_or_b32_e32 v4, 0x66, v1
	s_nop 0
	v_writelane_b32 v255, s0, 13
	s_nop 1
	v_writelane_b32 v255, s1, 14
	v_cmp_gt_u32_e64 s[0:1], v4, v3
	v_or_b32_e32 v4, 0x65, v1
	s_nop 0
	v_writelane_b32 v255, s0, 15
	s_nop 1
	v_writelane_b32 v255, s1, 16
	v_cmp_gt_u32_e64 s[0:1], v4, v3
	v_or_b32_e32 v4, 0x64, v1
	s_nop 0
	v_writelane_b32 v255, s0, 17
	s_nop 1
	v_writelane_b32 v255, s1, 18
	v_cmp_gt_u32_e64 s[0:1], v4, v3
	v_or_b32_e32 v4, 0x63, v1
	s_nop 0
	v_writelane_b32 v255, s0, 19
	s_nop 1
	v_writelane_b32 v255, s1, 20
	v_cmp_gt_u32_e64 s[0:1], v4, v3
	v_or_b32_e32 v4, 0x62, v1
	s_nop 0
	v_writelane_b32 v255, s0, 21
	s_nop 1
	v_writelane_b32 v255, s1, 22
	v_cmp_gt_u32_e64 s[0:1], v4, v3
	v_or_b32_e32 v4, 0x61, v1
	s_nop 0
	v_writelane_b32 v255, s0, 23
	s_nop 1
	v_writelane_b32 v255, s1, 24
	v_cmp_gt_u32_e64 s[0:1], v4, v3
	v_or_b32_e32 v4, 0x60, v1
	s_nop 0
	v_writelane_b32 v255, s0, 25
	s_nop 1
	v_writelane_b32 v255, s1, 26
	v_cmp_gt_u32_e64 s[0:1], v4, v3
	v_or_b32_e32 v4, 0x77, v1
	s_nop 0
	v_writelane_b32 v255, s0, 27
	s_nop 1
	v_writelane_b32 v255, s1, 28
	v_cmp_gt_u32_e64 s[0:1], v4, v3
	v_or_b32_e32 v4, 0x76, v1
	s_nop 0
	v_writelane_b32 v255, s0, 29
	s_nop 1
	v_writelane_b32 v255, s1, 30
	v_cmp_gt_u32_e64 s[0:1], v4, v3
	v_or_b32_e32 v4, 0x75, v1
	s_nop 0
	v_writelane_b32 v255, s0, 31
	s_nop 1
	v_writelane_b32 v255, s1, 32
	v_cmp_gt_u32_e64 s[0:1], v4, v3
	v_or_b32_e32 v4, 0x74, v1
	v_cmp_gt_u32_e64 s[2:3], v4, v3
	v_writelane_b32 v255, s0, 33
	v_or_b32_e32 v4, 0x73, v1
	v_cmp_gt_u32_e64 s[40:41], v4, v3
	v_writelane_b32 v255, s1, 34
	v_readlane_b32 s0, v253, 10
	v_or_b32_e32 v4, 0x72, v1
	s_add_i32 s17, s0, s14
	s_lshl_b32 s14, s83, 3
	v_readlane_b32 s0, v253, 11
	v_cmp_gt_u32_e64 s[6:7], v4, v3
	v_or_b32_e32 v4, 0x71, v1
	v_or_b32_e32 v1, 0x70, v1
	s_add_i32 s18, s0, s14
	v_readlane_b32 s14, v253, 39
	v_readlane_b32 s0, v252, 21
	v_cmp_gt_u32_e64 s[8:9], v4, v3
	v_cmp_gt_u32_e64 s[10:11], v1, v3
	s_mov_b32 s26, s14
	v_readlane_b32 s1, v252, 22
	v_readlane_b32 s15, v253, 40

.LBB0_126:
	v_readlane_b32 s0, v252, 48
	v_readlane_b32 s1, v252, 49
	s_andn2_b64 vcc, exec, s[0:1]
	s_barrier
	s_cbranch_vccnz .LBB0_227
	v_readlane_b32 s0, v255, 61
	s_nop 3
	s_cmp_eq_u32 s0, 2
	s_cbranch_scc1 .LBB0_227
	s_lshl_b64 s[0:1], s[94:95], 2
	v_readlane_b32 s2, v252, 25
	s_add_u32 s8, s2, s0
	v_readlane_b32 s0, v252, 26
	s_addc_u32 s9, s0, s1
	s_lshl_b32 s0, s94, 7
	v_ashrrev_i32_e32 v1, 6, v200
	s_ashr_i32 s1, s0, 31
	v_lshlrev_b32_e32 v0, 5, v1
	s_lshl_b64 s[0:1], s[0:1], 2
	v_readlane_b32 s2, v252, 27
	v_ashrrev_i32_e32 v203, 31, v0
	v_or_b32_e32 v202, v0, v157
	v_lshrrev_b32_e32 v0, 2, v200
	s_add_u32 s10, s2, s0
	v_readlane_b32 s0, v252, 28
	v_and_b32_e32 v0, 8, v0
	v_readlane_b32 s2, v253, 33
	s_addc_u32 s11, s0, s1
	v_cmp_eq_u32_e64 s[0:1], 0, v244
	v_lshl_add_u32 v195, v1, 2, s2
	v_lshlrev_b32_e32 v201, 8, v244
	v_lshlrev_b32_e32 v192, 1, v0
	v_readlane_b32 s20, v252, 47
	v_readlane_b32 s32, v255, 61
	s_nop 3
	s_cmp_lg_u32 s32, 3
	s_cbranch_scc1 .Lgd_first
	v_readlane_b32 s20, v255, 59
	s_nop 3
	s_cmpk_gt_i32 s20, 0x3ff
	s_cbranch_scc1 .LBB0_227
.Lgd_first:
	s_branch .LBB0_129
.LBB0_128:
	s_or_b64 exec, exec, s[4:5]
	s_cmp_lg_u32 s13, 0
	s_cbranch_scc1 .Ltk_skip0
	s_mov_b64 s[4:5], exec
	s_mov_b64 exec, 1
	v_mov_b32_e32 v96, 1
	global_atomic_add v96, v193, v96, s[8:9] sc0
	s_mov_b64 exec, s[4:5]

.Ltk_skip1:
	s_waitcnt lgkmcnt(0)
	s_barrier
	v_mov_b32_e32 v97, s68
	ds_read_b32 v196, v97
	s_waitcnt lgkmcnt(0)
	v_readfirstlane_b32 s20, v196
	v_readlane_b32 s32, v255, 61
	s_nop 3
	s_cmp_lg_u32 s32, 1
	s_cbranch_scc1 .Lgd_nodefer
	v_readlane_b32 s32, v255, 60
	s_nop 3
	s_sub_i32 s32, s32, 1
	s_nop 0
	v_writelane_b32 v255, s32, 60
	v_writelane_b32 v255, s20, 59
	s_cmp_lg_u32 s32, 0
	s_cbranch_scc0 .LBB0_227
.Lgd_nodefer:
	s_cmpk_gt_i32 s20, 0x3ff
	s_cbranch_scc1 .LBB0_227

.LBB0_342:
	v_readlane_b32 s0, v255, 61
	s_nop 3
	s_cmp_eq_u32 s0, 1
	s_cbranch_scc1 .Lgd_adv
	s_cmp_eq_u32 s0, 2
	s_cbranch_scc0 .Lmx_next
.Lgd_adv:
	s_add_i32 s0, s0, 1
	s_nop 0
	v_writelane_b32 v255, s0, 61
	s_waitcnt vmcnt(0) lgkmcnt(0)
	s_barrier
	s_branch .LBB0_24
.Lmx_next:
	s_add_i32 s1, s20, 1
	s_and_b32 s1, s1, 3
	s_cmp_eq_u32 s1, 3
	s_cselect_b32 s1, 1, 0
	v_readlane_b32 s0, v253, 46
	s_nop 3
	s_bfe_u32 s0, s0, 0x20003
	s_lshl_b32 s0, s0, 2
	s_lshr_b32 s0, 0x1111, s0
	s_and_b32 s0, s0, 15
	s_cmp_lg_u32 s0, 0
	s_cselect_b32 s2, 1, 0
	s_and_b32 s1, s1, s2
	s_nop 0
	v_writelane_b32 v255, s1, 61
	v_writelane_b32 v255, s0, 60
	s_add_i32 s20, s20, 1
	s_cmp_ge_i32 s20, s21
	s_mov_b64 s[0:1], -1
	s_cbranch_scc1 .LBB0_23
	s_waitcnt vmcnt(0)
	s_waitcnt vmcnt(0) lgkmcnt(0)
	s_barrier
	s_mov_b64 s[0:1], exec
	v_readlane_b32 s2, v251, 14
	v_readlane_b32 s3, v251, 15
	s_and_b64 s[2:3], s[0:1], s[2:3]
	s_mov_b64 exec, s[2:3]
	s_cbranch_execz .LBB0_22
	v_readlane_b32 s2, v253, 31
	s_waitcnt vmcnt(0) expcnt(0) lgkmcnt(0)
	s_nop 0
	v_mov_b32_e32 v0, s2
	ds_read_b32 v2, v0
	v_readlane_b32 s2, v253, 32
	s_waitcnt lgkmcnt(0)
	v_cmp_ne_u32_e32 vcc, 0, v2
	v_mov_b32_e32 v0, s2
	ds_read_b32 v0, v0
	s_cbranch_vccnz .LBB0_359
	v_readlane_b32 s4, v251, 12
	v_readlane_b32 s5, v251, 13
	s_load_dwordx2 s[2:3], s[4:5], 0x4
	s_mov_b32 s9, 1
	s_waitcnt lgkmcnt(0)
	s_mul_i32 s8, s2, s65
	s_mul_i32 s8, s8, s3
	s_branch .LBB0_347
